# tile-loop tails keep gridDim in a spill lane (no reload + vmcnt(0) per tile); gain-vector loads of the q/k head-norm tiles hoisted (16 in flight)
# speedup vs baseline: 1.0132x; 1.0132x over previous
.LBB0_390:
	s_or_b64 exec, exec, s[0:1]
	v_readlane_b32 s0, v235, 16
	v_cndmask_b32_e64 v0, v204, v205, s[4:5]
	v_readlane_b32 s1, v235, 17
	s_waitcnt vmcnt(2) lgkmcnt(7)
	v_and_b32_e32 v71, 0xffff0000, v30
	v_lshlrev_b32_e32 v70, 16, v30
	v_lshl_add_u64 v[36:37], s[0:1], 0, v[0:1]
	v_readlane_b32 s0, v235, 15
	v_lshlrev_b32_e32 v72, 16, v31
	v_and_b32_e32 v73, 0xffff0000, v31
	v_mov_b32_e32 v0, s0
	v_readlane_b32 s0, v235, 14
	v_cndmask_b32_e32 v37, v37, v0, vcc
	v_lshlrev_b32_e32 v74, 16, v32
	v_mov_b32_e32 v0, s0
	v_cndmask_b32_e32 v36, v36, v0, vcc
	global_load_dwordx4 v[76:79], v[36:37], off
	global_load_dwordx4 v[80:83], v[36:37], off offset:16
	global_load_dwordx4 v[84:87], v[36:37], off offset:32
	global_load_dwordx4 v[88:91], v[36:37], off offset:48
	global_load_dwordx4 v[92:95], v[36:37], off offset:64
	global_load_dwordx4 v[96:99], v[36:37], off offset:80
	global_load_dwordx4 v[100:103], v[36:37], off offset:96
	global_load_dwordx4 v[104:107], v[36:37], off offset:112
	global_load_dwordx4 v[108:111], v[36:37], off offset:128
	global_load_dwordx4 v[112:115], v[36:37], off offset:144
	global_load_dwordx4 v[116:119], v[36:37], off offset:160
	global_load_dwordx4 v[120:123], v[36:37], off offset:176
	global_load_dwordx4 v[124:127], v[36:37], off offset:192
	global_load_dwordx4 v[128:131], v[36:37], off offset:208
	global_load_dwordx4 v[138:141], v[36:37], off offset:224
	global_load_dwordx4 v[142:145], v[36:37], off offset:240
	v_mul_f32_e32 v0, v71, v71
	v_fmac_f32_e32 v0, v70, v70
	v_fmac_f32_e32 v0, v72, v72
	v_fmac_f32_e32 v0, v73, v73
	v_and_b32_e32 v69, 0xffff0000, v32
	v_fmac_f32_e32 v0, v74, v74
	v_lshlrev_b32_e32 v68, 16, v33
	v_fmac_f32_e32 v0, v69, v69
	v_and_b32_e32 v67, 0xffff0000, v33
	v_fmac_f32_e32 v0, v68, v68
	s_waitcnt lgkmcnt(6)
	v_lshlrev_b32_e32 v66, 16, v26
	v_fmac_f32_e32 v0, v67, v67
	v_and_b32_e32 v65, 0xffff0000, v26
	v_fmac_f32_e32 v0, v66, v66
	v_lshlrev_b32_e32 v64, 16, v27
	v_fmac_f32_e32 v0, v65, v65
	v_and_b32_e32 v63, 0xffff0000, v27
	v_fmac_f32_e32 v0, v64, v64
	v_lshlrev_b32_e32 v62, 16, v28
	v_fmac_f32_e32 v0, v63, v63
	v_and_b32_e32 v61, 0xffff0000, v28
	v_fmac_f32_e32 v0, v62, v62
	v_lshlrev_b32_e32 v60, 16, v29
	v_fmac_f32_e32 v0, v61, v61
	v_and_b32_e32 v59, 0xffff0000, v29
	v_fmac_f32_e32 v0, v60, v60
	s_waitcnt lgkmcnt(5)
	v_lshlrev_b32_e32 v58, 16, v22
	v_fmac_f32_e32 v0, v59, v59
	v_and_b32_e32 v57, 0xffff0000, v22
	v_fmac_f32_e32 v0, v58, v58
	v_lshlrev_b32_e32 v56, 16, v23
	v_fmac_f32_e32 v0, v57, v57
	v_and_b32_e32 v55, 0xffff0000, v23
	v_fmac_f32_e32 v0, v56, v56
	v_lshlrev_b32_e32 v54, 16, v24
	v_fmac_f32_e32 v0, v55, v55
	v_and_b32_e32 v52, 0xffff0000, v24
	v_fmac_f32_e32 v0, v54, v54
	v_lshlrev_b32_e32 v51, 16, v25
	v_fmac_f32_e32 v0, v52, v52
	v_and_b32_e32 v50, 0xffff0000, v25
	v_fmac_f32_e32 v0, v51, v51
	s_waitcnt lgkmcnt(4)
	v_lshlrev_b32_e32 v49, 16, v18
	v_fmac_f32_e32 v0, v50, v50
	v_and_b32_e32 v48, 0xffff0000, v18
	v_fmac_f32_e32 v0, v49, v49
	v_lshlrev_b32_e32 v47, 16, v19
	v_fmac_f32_e32 v0, v48, v48
	v_and_b32_e32 v46, 0xffff0000, v19
	v_fmac_f32_e32 v0, v47, v47
	v_lshlrev_b32_e32 v45, 16, v20
	v_fmac_f32_e32 v0, v46, v46
	v_and_b32_e32 v44, 0xffff0000, v20
	v_fmac_f32_e32 v0, v45, v45
	v_lshlrev_b32_e32 v43, 16, v21
	v_fmac_f32_e32 v0, v44, v44
	v_and_b32_e32 v42, 0xffff0000, v21
	v_fmac_f32_e32 v0, v43, v43
	s_waitcnt lgkmcnt(3)
	v_lshlrev_b32_e32 v41, 16, v14
	v_fmac_f32_e32 v0, v42, v42
	v_and_b32_e32 v40, 0xffff0000, v14
	v_fmac_f32_e32 v0, v41, v41
	v_lshlrev_b32_e32 v39, 16, v15
	v_fmac_f32_e32 v0, v40, v40
	v_and_b32_e32 v38, 0xffff0000, v15
	v_fmac_f32_e32 v0, v39, v39
	v_lshlrev_b32_e32 v33, 16, v16
	v_fmac_f32_e32 v0, v38, v38
	v_and_b32_e32 v32, 0xffff0000, v16
	v_fmac_f32_e32 v0, v33, v33
	v_lshlrev_b32_e32 v31, 16, v17
	v_fmac_f32_e32 v0, v32, v32
	v_and_b32_e32 v30, 0xffff0000, v17
	v_fmac_f32_e32 v0, v31, v31
	s_waitcnt lgkmcnt(2)
	v_lshlrev_b32_e32 v29, 16, v10
	v_fmac_f32_e32 v0, v30, v30
	v_and_b32_e32 v28, 0xffff0000, v10
	v_fmac_f32_e32 v0, v29, v29
	v_lshlrev_b32_e32 v27, 16, v11
	v_fmac_f32_e32 v0, v28, v28
	v_and_b32_e32 v26, 0xffff0000, v11
	v_fmac_f32_e32 v0, v27, v27
	v_lshlrev_b32_e32 v25, 16, v12
	v_fmac_f32_e32 v0, v26, v26
	v_and_b32_e32 v24, 0xffff0000, v12
	v_fmac_f32_e32 v0, v25, v25
	v_lshlrev_b32_e32 v23, 16, v13
	v_fmac_f32_e32 v0, v24, v24
	v_and_b32_e32 v22, 0xffff0000, v13
	v_fmac_f32_e32 v0, v23, v23
	s_waitcnt lgkmcnt(1)
	v_lshlrev_b32_e32 v21, 16, v6
	v_fmac_f32_e32 v0, v22, v22
	v_and_b32_e32 v20, 0xffff0000, v6
	v_fmac_f32_e32 v0, v21, v21
	v_lshlrev_b32_e32 v19, 16, v7
	v_fmac_f32_e32 v0, v20, v20
	v_and_b32_e32 v18, 0xffff0000, v7
	v_fmac_f32_e32 v0, v19, v19
	v_lshlrev_b32_e32 v17, 16, v8
	v_fmac_f32_e32 v0, v18, v18
	v_and_b32_e32 v16, 0xffff0000, v8
	v_lshlrev_b32_e32 v15, 16, v9
	v_and_b32_e32 v14, 0xffff0000, v9
	v_fmac_f32_e32 v0, v17, v17
	s_waitcnt lgkmcnt(0)
	v_lshlrev_b32_e32 v13, 16, v2
	v_and_b32_e32 v12, 0xffff0000, v2
	v_lshlrev_b32_e32 v11, 16, v3
	v_and_b32_e32 v10, 0xffff0000, v3
	v_fmac_f32_e32 v0, v16, v16
	v_pk_mul_f32 v[2:3], v[14:15], v[14:15]
	v_lshlrev_b32_e32 v9, 16, v4
	v_add_f32_e32 v0, v3, v0
	v_add_f32_e32 v0, v2, v0
	v_pk_mul_f32 v[2:3], v[12:13], v[12:13]
	v_and_b32_e32 v8, 0xffff0000, v4
	v_add_f32_e32 v0, v3, v0
	v_add_f32_e32 v0, v2, v0
	v_pk_mul_f32 v[2:3], v[10:11], v[10:11]
	v_lshlrev_b32_e32 v7, 16, v5
	v_add_f32_e32 v0, v3, v0
	v_add_f32_e32 v0, v2, v0
	v_pk_mul_f32 v[2:3], v[8:9], v[8:9]
	v_and_b32_e32 v6, 0xffff0000, v5
	v_add_f32_e32 v0, v3, v0
	v_add_f32_e32 v0, v2, v0
	v_pk_mul_f32 v[2:3], v[6:7], v[6:7]
	s_mov_b32 s0, 0x800000
	v_add_f32_e32 v0, v3, v0
	v_add_f32_e32 v0, v2, v0
	v_fmamk_f32 v0, v0, 0x3c800000, v167
	v_cmp_gt_f32_e32 vcc, s0, v0
	v_mul_f32_e32 v2, 0x4b800000, v0
	s_nop 0
	v_cndmask_b32_e32 v0, v0, v2, vcc
	v_rsq_f32_e32 v0, v0
	s_nop 0
	v_mul_f32_e32 v2, 0x45800000, v0
	v_cndmask_b32_e32 v0, v0, v2, vcc
	s_waitcnt vmcnt(0)
	s_nop 1
	v_mov_b32_e32 v2, v76
	v_mov_b32_e32 v3, v77
	v_mov_b32_e32 v4, v78
	v_mov_b32_e32 v5, v79
	v_mul_f32_e32 v0, v53, v0
	v_mul_f32_e32 v53, v0, v70
	v_mul_f32_e32 v50, v0, v50
	v_mul_f32_e32 v49, v0, v49
	v_mul_f32_e32 v48, v0, v48
	v_mul_f32_e32 v42, v0, v42
	v_mul_f32_e32 v41, v0, v41
	v_mul_f32_e32 v40, v0, v40
	v_mul_f32_e32 v30, v0, v30
	v_mul_f32_e32 v29, v0, v29
	v_mul_f32_e32 v28, v0, v28
	v_mul_f32_e32 v22, v0, v22
	v_mul_f32_e32 v21, v0, v21
	v_mul_f32_e32 v20, v0, v20
	v_mul_f32_e32 v14, v0, v14
	v_mul_f32_e32 v13, v0, v13
	v_mul_f32_e32 v12, v0, v12
	v_mul_f32_e32 v2, v53, v2
	v_mul_f32_e32 v53, v0, v71
	v_mul_f32_e32 v3, v53, v3
	v_cvt_pk_bf16_f32 v2, v2, v3
	v_mul_f32_e32 v3, v0, v72
	v_mul_f32_e32 v3, v3, v4
	v_mul_f32_e32 v4, v0, v73
	s_nop 1
	v_mov_b32_e32 v70, v80
	v_mov_b32_e32 v71, v81
	v_mov_b32_e32 v72, v82
	v_mov_b32_e32 v73, v83
	v_mul_f32_e32 v4, v4, v5
	v_cvt_pk_bf16_f32 v3, v3, v4
	v_mul_f32_e32 v4, v0, v74
	v_mul_f32_e32 v5, v0, v69
	v_mul_f32_e32 v53, v0, v67
	v_mul_f32_e32 v4, v4, v70
	v_mul_f32_e32 v5, v5, v71
	v_cvt_pk_bf16_f32 v4, v4, v5
	v_mul_f32_e32 v5, v0, v68
	v_mul_f32_e32 v5, v5, v72
	v_mul_f32_e32 v53, v53, v73
	v_cvt_pk_bf16_f32 v5, v5, v53
	global_store_dwordx4 v[34:35], v[2:5], off
	s_nop 1
	v_mov_b32_e32 v2, v84
	v_mov_b32_e32 v3, v85
	v_mov_b32_e32 v4, v86
	v_mov_b32_e32 v5, v87
	v_mul_f32_e32 v53, v0, v66
	v_mul_f32_e32 v2, v53, v2
	v_mul_f32_e32 v53, v0, v65
	v_mul_f32_e32 v3, v53, v3
	v_cvt_pk_bf16_f32 v2, v2, v3
	v_mul_f32_e32 v3, v0, v64
	v_mul_f32_e32 v3, v3, v4
	v_mul_f32_e32 v4, v0, v63
	v_mul_f32_e32 v4, v4, v5
	v_cvt_pk_bf16_f32 v3, v3, v4
	v_mul_f32_e32 v4, v0, v62
	s_nop 1
	v_mov_b32_e32 v62, v88
	v_mov_b32_e32 v63, v89
	v_mov_b32_e32 v64, v90
	v_mov_b32_e32 v65, v91
	v_mul_f32_e32 v5, v0, v61
	v_mul_f32_e32 v53, v0, v59
	v_mul_f32_e32 v4, v4, v62
	v_mul_f32_e32 v5, v5, v63
	v_cvt_pk_bf16_f32 v4, v4, v5
	v_mul_f32_e32 v5, v0, v60
	v_mul_f32_e32 v5, v5, v64
	v_mul_f32_e32 v53, v53, v65
	v_cvt_pk_bf16_f32 v5, v5, v53
	global_store_dwordx4 v[34:35], v[2:5], off offset:16
	s_nop 1
	v_mov_b32_e32 v2, v92
	v_mov_b32_e32 v3, v93
	v_mov_b32_e32 v4, v94
	v_mov_b32_e32 v5, v95
	v_mul_f32_e32 v53, v0, v58
	v_mul_f32_e32 v2, v53, v2
	v_mul_f32_e32 v53, v0, v57
	v_mul_f32_e32 v3, v53, v3
	v_cvt_pk_bf16_f32 v2, v2, v3
	v_mul_f32_e32 v3, v0, v56
	v_mul_f32_e32 v3, v3, v4
	v_mul_f32_e32 v4, v0, v55
	v_mul_f32_e32 v4, v4, v5
	v_cvt_pk_bf16_f32 v3, v3, v4
	v_mul_f32_e32 v4, v0, v54
	s_nop 1
	v_mov_b32_e32 v54, v96
	v_mov_b32_e32 v55, v97
	v_mov_b32_e32 v56, v98
	v_mov_b32_e32 v57, v99
	v_mul_f32_e32 v5, v0, v52
	v_mul_f32_e32 v4, v4, v54
	v_mul_f32_e32 v5, v5, v55
	v_cvt_pk_bf16_f32 v4, v4, v5
	v_mul_f32_e32 v5, v0, v51
	v_mul_f32_e32 v5, v5, v56
	v_mul_f32_e32 v50, v50, v57
	v_cvt_pk_bf16_f32 v5, v5, v50
	global_store_dwordx4 v[34:35], v[2:5], off offset:32
	s_nop 1
	v_mov_b32_e32 v2, v100
	v_mov_b32_e32 v3, v101
	v_mov_b32_e32 v4, v102
	v_mov_b32_e32 v5, v103
	v_mul_f32_e32 v2, v49, v2
	v_mul_f32_e32 v3, v48, v3
	v_cvt_pk_bf16_f32 v2, v2, v3
	v_mul_f32_e32 v3, v0, v47
	v_mul_f32_e32 v3, v3, v4
	v_mul_f32_e32 v4, v0, v46
	s_nop 1
	v_mov_b32_e32 v46, v104
	v_mov_b32_e32 v47, v105
	v_mov_b32_e32 v48, v106
	v_mov_b32_e32 v49, v107
	v_mul_f32_e32 v4, v4, v5
	v_cvt_pk_bf16_f32 v3, v3, v4
	v_mul_f32_e32 v4, v0, v45
	v_mul_f32_e32 v5, v0, v44
	v_mul_f32_e32 v4, v4, v46
	v_mul_f32_e32 v5, v5, v47
	v_cvt_pk_bf16_f32 v4, v4, v5
	v_mul_f32_e32 v5, v0, v43
	v_mul_f32_e32 v5, v5, v48
	v_mul_f32_e32 v42, v42, v49
	v_cvt_pk_bf16_f32 v5, v5, v42
	global_store_dwordx4 v[34:35], v[2:5], off offset:48
	s_nop 1
	v_mov_b32_e32 v2, v108
	v_mov_b32_e32 v3, v109
	v_mov_b32_e32 v4, v110
	v_mov_b32_e32 v5, v111
	v_mul_f32_e32 v2, v41, v2
	v_mul_f32_e32 v3, v40, v3
	v_cvt_pk_bf16_f32 v2, v2, v3
	v_mul_f32_e32 v3, v0, v39
	v_mul_f32_e32 v3, v3, v4
	v_mul_f32_e32 v4, v0, v38
	s_nop 1
	v_mov_b32_e32 v38, v112
	v_mov_b32_e32 v39, v113
	v_mov_b32_e32 v40, v114
	v_mov_b32_e32 v41, v115
	v_mul_f32_e32 v4, v4, v5
	v_cvt_pk_bf16_f32 v3, v3, v4
	v_mul_f32_e32 v4, v0, v33
	v_mul_f32_e32 v5, v0, v32
	v_mul_f32_e32 v4, v4, v38
	v_mul_f32_e32 v5, v5, v39
	v_cvt_pk_bf16_f32 v4, v4, v5
	v_mul_f32_e32 v5, v0, v31
	v_mul_f32_e32 v5, v5, v40
	v_mul_f32_e32 v30, v30, v41
	v_cvt_pk_bf16_f32 v5, v5, v30
	global_store_dwordx4 v[34:35], v[2:5], off offset:64
	s_nop 1
	v_mov_b32_e32 v2, v116
	v_mov_b32_e32 v3, v117
	v_mov_b32_e32 v4, v118
	v_mov_b32_e32 v5, v119
	v_mul_f32_e32 v2, v29, v2
	v_mul_f32_e32 v3, v28, v3
	v_cvt_pk_bf16_f32 v2, v2, v3
	v_mul_f32_e32 v3, v0, v27
	v_mul_f32_e32 v3, v3, v4
	v_mul_f32_e32 v4, v0, v26
	s_nop 1
	v_mov_b32_e32 v26, v120
	v_mov_b32_e32 v27, v121
	v_mov_b32_e32 v28, v122
	v_mov_b32_e32 v29, v123
	v_mul_f32_e32 v4, v4, v5
	v_cvt_pk_bf16_f32 v3, v3, v4
	v_mul_f32_e32 v4, v0, v25
	v_mul_f32_e32 v5, v0, v24
	v_mul_f32_e32 v4, v4, v26
	v_mul_f32_e32 v5, v5, v27
	v_cvt_pk_bf16_f32 v4, v4, v5
	v_mul_f32_e32 v5, v0, v23
	v_mul_f32_e32 v5, v5, v28
	v_mul_f32_e32 v22, v22, v29
	v_cvt_pk_bf16_f32 v5, v5, v22
	global_store_dwordx4 v[34:35], v[2:5], off offset:80
	s_nop 1
	v_mov_b32_e32 v2, v124
	v_mov_b32_e32 v3, v125
	v_mov_b32_e32 v4, v126
	v_mov_b32_e32 v5, v127
	v_mul_f32_e32 v2, v21, v2
	v_mul_f32_e32 v3, v20, v3
	v_cvt_pk_bf16_f32 v2, v2, v3
	v_mul_f32_e32 v3, v0, v19
	v_mul_f32_e32 v3, v3, v4
	v_mul_f32_e32 v4, v0, v18
	s_nop 1
	v_mov_b32_e32 v18, v128
	v_mov_b32_e32 v19, v129
	v_mov_b32_e32 v20, v130
	v_mov_b32_e32 v21, v131
	v_mul_f32_e32 v4, v4, v5
	v_cvt_pk_bf16_f32 v3, v3, v4
	v_mul_f32_e32 v4, v0, v17
	v_mul_f32_e32 v5, v0, v16
	v_mul_f32_e32 v4, v4, v18
	v_mul_f32_e32 v5, v5, v19
	v_cvt_pk_bf16_f32 v4, v4, v5
	v_mul_f32_e32 v5, v0, v15
	v_mul_f32_e32 v5, v5, v20
	v_mul_f32_e32 v14, v14, v21
	v_cvt_pk_bf16_f32 v5, v5, v14
	global_store_dwordx4 v[34:35], v[2:5], off offset:96
	s_nop 1
	v_mov_b32_e32 v2, v138
	v_mov_b32_e32 v3, v139
	v_mov_b32_e32 v4, v140
	v_mov_b32_e32 v5, v141
	v_mul_f32_e32 v2, v13, v2
	v_mul_f32_e32 v3, v12, v3
	v_cvt_pk_bf16_f32 v2, v2, v3
	v_mul_f32_e32 v3, v0, v11
	v_mul_f32_e32 v3, v3, v4
	v_mul_f32_e32 v4, v0, v10
	s_nop 1
	v_mov_b32_e32 v10, v142
	v_mov_b32_e32 v11, v143
	v_mov_b32_e32 v12, v144
	v_mov_b32_e32 v13, v145
	v_mul_f32_e32 v4, v4, v5
	v_cvt_pk_bf16_f32 v3, v3, v4
	v_mul_f32_e32 v4, v0, v9
	v_mul_f32_e32 v5, v0, v8
	v_mul_f32_e32 v4, v4, v10
	v_mul_f32_e32 v5, v5, v11
	v_cvt_pk_bf16_f32 v4, v4, v5
	v_mul_f32_e32 v5, v0, v7
	v_mul_f32_e32 v5, v5, v12
	v_mul_f32_e32 v0, v0, v6
	v_mul_f32_e32 v0, v0, v13
	v_cvt_pk_bf16_f32 v5, v5, v0
	global_store_dwordx4 v[34:35], v[2:5], off offset:112
